# adds: conv fast path pairs adjacent row groups 2*bid and 2*bid+1 (3 of 7 raw rows of the second group now L1/L2 hits)
# speedup vs baseline: 1.0368x; 1.0016x over previous
.LBB0_213:
	s_or_b64 exec, exec, s[0:1]
	v_readlane_b32 s36, v254, 5
	v_readlane_b32 s40, v254, 9
	v_readlane_b32 s41, v254, 10
	v_readlane_b32 s42, v254, 11
	v_readlane_b32 s43, v254, 12
	v_readlane_b32 s44, v254, 13
	v_readlane_b32 s45, v254, 14
	v_readlane_b32 s46, v254, 15
	v_readlane_b32 s47, v254, 16
	v_readlane_b32 s48, v254, 17
	v_readlane_b32 s49, v254, 18
	v_readlane_b32 s50, v254, 19
	v_readlane_b32 s51, v254, 20
	s_mov_b64 s[20:21], s[40:41]
	v_mov_b32_e32 v4, v0
	s_mov_b64 s[28:29], s[48:49]
	s_waitcnt lgkmcnt(0)
	s_barrier
	s_mov_b64 s[2:3], s[74:75]
	s_waitcnt vmcnt(7)
	v_lshlrev_b32_e32 v30, 2, v4
	v_mov_b32_e32 v2, s28
	v_mov_b32_e32 v3, s29
	s_add_u32 s0, s2, 0x8a6e000
	v_ashrrev_i32_e32 v31, 31, v30
	s_addc_u32 s1, s3, 0
	v_lshl_add_u64 v[32:33], v[30:31], 2, v[2:3]
	s_mov_b64 s[4:5], 0x2000
	s_movk_i32 s8, 0x100
	v_lshl_add_u64 v[34:35], v[32:33], 0, s[4:5]
	s_mov_b64 s[4:5], 0x4000
	s_add_u32 s6, s2, 0x1b36e000
	v_lshl_add_u64 v[36:37], v[32:33], 0, s[4:5]
	s_mov_b64 s[4:5], 0x6000
	s_addc_u32 s7, s3, 0
	v_mov_b32_e32 v2, 0x3d800000
	v_cmp_gt_i32_e32 vcc, s8, v4
	v_lshl_add_u64 v[38:39], v[32:33], 0, s[4:5]
	s_cmpk_gt_i32 s14, 0xfff
	v_cndmask_b32_e64 v64, v2, 1.0, vcc
	v_readlane_b32 s37, v254, 6
	v_readlane_b32 s38, v254, 7
	v_readlane_b32 s39, v254, 8
	s_mov_b64 s[22:23], s[42:43]
	s_mov_b64 s[24:25], s[44:45]
	s_mov_b64 s[26:27], s[46:47]
	s_mov_b64 s[30:31], s[50:51]
	s_cbranch_scc1 .LBB0_248
	v_readlane_b32 s36, v254, 5
	global_load_dwordx4 v[2:5], v[32:33], off
	global_load_dwordx4 v[6:9], v[34:35], off
	global_load_dwordx4 v[10:13], v[36:37], off
	global_load_dwordx4 v[14:17], v[38:39], off
	v_readlane_b32 s50, v254, 19
	v_readlane_b32 s51, v254, 20
	v_readlane_b32 s2, v254, 0
	v_readlane_b32 s3, v254, 1
	s_waitcnt vmcnt(8)
	v_lshl_add_u64 v[18:19], v[30:31], 2, s[50:51]
	global_load_dwordx4 v[18:21], v[18:19], off
	s_load_dword s2, s[2:3], 0x10
	v_lshlrev_b64 v[24:25], 1, v[30:31]
	v_lshl_add_u64 v[22:23], s[0:1], 0, v[24:25]
	v_lshl_add_u64 v[24:25], s[6:7], 0, v[24:25]
	s_lshl_b32 s22, s14, 1
	s_waitcnt lgkmcnt(0)
	s_lshr_b32 s2, s2, 16
	s_cmp_lg_u32 s2, 0
	s_cselect_b64 s[2:3], -1, 0
	s_cmp_lg_u64 s[2:3], 0
	v_cndmask_b32_e64 v26, 0, 1, s[2:3]
	s_addc_u32 s12, s90, 0
	s_lshl_b32 s2, s14, 3
	s_or_b32 s8, s2, 3
	v_readfirstlane_b32 s2, v26
	s_lshl_b32 s21, s90, 2
	s_lshl_b32 s2, s2, 2
	s_lshl_b32 s13, s12, 3
	s_lshl_b32 s20, s12, 1
	s_add_i32 s21, s21, s2
	s_mov_b32 s21, 4
	v_readlane_b32 s37, v254, 6
	v_readlane_b32 s38, v254, 7
	v_readlane_b32 s39, v254, 8
	v_readlane_b32 s40, v254, 9
	v_readlane_b32 s41, v254, 10
	v_readlane_b32 s42, v254, 11
	v_readlane_b32 s43, v254, 12
	v_readlane_b32 s44, v254, 13
	v_readlane_b32 s45, v254, 14
	v_readlane_b32 s46, v254, 15
	v_readlane_b32 s47, v254, 16
	v_readlane_b32 s48, v254, 17
	v_readlane_b32 s49, v254, 18
	s_branch .LBB0_216

.LBB0_230:
	s_add_i32 s23, s22, 1
	s_cmpk_lt_i32 s23, 0x1000
	s_cselect_b64 s[2:3], -1, 0
	s_and_b32 s10, s23, 0x1ff
	s_cmp_lg_u32 s10, 0
	s_cselect_b64 s[10:11], -1, 0
	s_and_b64 s[2:3], s[2:3], s[10:11]
	v_cndmask_b32_e64 v27, 0, 1, s[2:3]
	s_and_b64 s[2:3], s[2:3], exec
	s_cselect_b32 s2, s23, s9
	s_lshl_b32 s10, s2, 2
	v_cmp_ne_u32_e64 s[2:3], 1, v27
	v_mov_b32_e32 v26, 0
	s_and_b64 vcc, exec, s[2:3]
	v_mov_b32_e32 v28, 0
	v_mov_b32_e32 v29, 0
	s_cbranch_vccnz .LBB0_242
	s_ashr_i32 s11, s10, 31
	s_lshl_b64 s[24:25], s[10:11], 12
	v_lshl_add_u64 v[28:29], v[22:23], 0, s[24:25]
	v_add_co_u32_e32 v28, vcc, 0xffffd000, v28
	s_nop 1
	v_addc_co_u32_e32 v29, vcc, -1, v29, vcc
	global_load_dwordx2 v[28:29], v[28:29], off
	s_and_b64 vcc, exec, s[2:3]
	v_mov_b32_e32 v42, 0
	v_mov_b32_e32 v43, 0
	s_cbranch_vccz .LBB0_243
